# full barriers: non-leader workgroups poll the global TOPGEN word directly (one hop less than via the per-XCD generation word)
# baseline (speedup 1.0000x reference)
; __device__ __forceinline__ unsigned xb_ld(unsigned* p)              { return __hip_atomic_load(p, __ATOMIC_RELAXED, __HIP_MEMORY_SCOPE_AGENT); }
; #define XB_SPIN(cond, bar) do { unsigned _sp = 0; while (cond) { __builtin_amdgcn_s_sleep(1); \
;     if ((++_sp & 255u) == 0u) { if (xb_ld(&(bar)[XB_TMO])) break; if (_sp > XB_SPIN_CAP) { atomicAdd(&(bar)[XB_TMO], 1u); break; } } } } while (0)
; __device__ __forceinline__ void xcd_barrier(const XcdBarrier& b) {
;     ...
;         } else {
;             XB_SPIN(xb_ld(&bar[XB_XGEN(b.x)]) == gen, bar);
;             __builtin_amdgcn_fence(__ATOMIC_ACQUIRE, "agent");
.LBB0_213:
	s_or_b64 exec, exec, s[2:3]
	v_cvt_f32_u32_e32 v6, v4
	s_waitcnt vmcnt(1)
	v_readfirstlane_b32 s2, v5
	v_sub_u32_e32 v5, 0, v4
	v_rcp_iflag_f32_e32 v6, v6
	v_add_u32_e32 v7, s2, v3
	v_mul_f32_e32 v6, 0x4f7ffffe, v6
	v_cvt_u32_f32_e32 v6, v6
	v_mul_lo_u32 v3, v5, v6
	v_mul_hi_u32 v3, v6, v3
	v_add_u32_e32 v3, v6, v3
	v_mul_hi_u32 v3, v7, v3
	v_mul_lo_u32 v5, v3, v4
	v_sub_u32_e32 v5, v7, v5
	v_add_u32_e32 v6, 1, v3
	v_cmp_ge_u32_e32 vcc, v5, v4
	s_nop 1
	v_cndmask_b32_e32 v3, v3, v6, vcc
	v_sub_u32_e32 v6, v5, v4
	v_cndmask_b32_e32 v5, v5, v6, vcc
	v_add_u32_e32 v6, 1, v3
	v_cmp_ge_u32_e32 vcc, v5, v4
	v_add_u32_e32 v5, 1, v7
	s_nop 0
	v_cndmask_b32_e32 v3, v3, v6, vcc
	v_mul_lo_u32 v6, v4, v3
	v_add_u32_e32 v4, v6, v4
	v_cmp_ne_u32_e32 vcc, v5, v4
	s_and_saveexec_b64 s[2:3], vcc
	s_xor_b64 s[2:3], exec, s[2:3]
	s_cbranch_execz .LBB0_227
	v_readlane_b32 s4, v251, 34
	v_readlane_b32 s5, v251, 35
	s_waitcnt lgkmcnt(0)
	s_nop 3
	global_load_dword v2, v99, s[4:5] sc1
	s_waitcnt vmcnt(0)
	v_cmp_eq_u32_e32 vcc, v2, v3
	s_and_saveexec_b64 s[4:5], vcc
	s_cbranch_execz .LBB0_226
	s_mov_b32 s10, 1
	s_mov_b64 s[8:9], 0
	s_branch .LBB0_217

; __device__ __forceinline__ unsigned xb_ld(unsigned* p)              { return __hip_atomic_load(p, __ATOMIC_RELAXED, __HIP_MEMORY_SCOPE_AGENT); }
; #define XB_SPIN(cond, bar) do { unsigned _sp = 0; while (cond) { __builtin_amdgcn_s_sleep(1); \
;     if ((++_sp & 255u) == 0u) { if (xb_ld(&(bar)[XB_TMO])) break; if (_sp > XB_SPIN_CAP) { atomicAdd(&(bar)[XB_TMO], 1u); break; } } } } while (0)
; __device__ __forceinline__ void xcd_barrier(const XcdBarrier& b) {
;     ...
;             XB_SPIN(xb_ld(&bar[XB_XGEN(b.x)]) == gen, bar);
.LBB0_219:
	v_readlane_b32 s14, v251, 34
	v_readlane_b32 s15, v251, 35
	s_add_i32 s10, s10, 1
	s_mov_b64 s[16:17], -1
	s_nop 2
	global_load_dword v2, v99, s[14:15] sc1
	s_waitcnt vmcnt(0)
	v_cmp_ne_u32_e32 vcc, v2, v3
	s_orn2_b64 s[14:15], vcc, exec
	s_branch .LBB0_216

; __device__ __forceinline__ unsigned xb_ld(unsigned* p)              { return __hip_atomic_load(p, __ATOMIC_RELAXED, __HIP_MEMORY_SCOPE_AGENT); }
; #define XB_SPIN(cond, bar) do { unsigned _sp = 0; while (cond) { __builtin_amdgcn_s_sleep(1); \
;     if ((++_sp & 255u) == 0u) { if (xb_ld(&(bar)[XB_TMO])) break; if (_sp > XB_SPIN_CAP) { atomicAdd(&(bar)[XB_TMO], 1u); break; } } } } while (0)
; __device__ __forceinline__ void xcd_barrier(const XcdBarrier& b) {
;     ...
;         } else {
;             XB_SPIN(xb_ld(&bar[XB_XGEN(b.x)]) == gen, bar);
;             __builtin_amdgcn_fence(__ATOMIC_ACQUIRE, "agent");
.LBB0_589:
	s_or_b64 exec, exec, s[4:5]
	v_cvt_f32_u32_e32 v6, v4
	s_waitcnt vmcnt(1)
	v_readfirstlane_b32 s4, v5
	v_sub_u32_e32 v5, 0, v4
	v_rcp_iflag_f32_e32 v6, v6
	v_add_u32_e32 v7, s4, v3
	v_mul_f32_e32 v6, 0x4f7ffffe, v6
	v_cvt_u32_f32_e32 v6, v6
	v_mul_lo_u32 v3, v5, v6
	v_mul_hi_u32 v3, v6, v3
	v_add_u32_e32 v3, v6, v3
	v_mul_hi_u32 v3, v7, v3
	v_mul_lo_u32 v5, v3, v4
	v_sub_u32_e32 v5, v7, v5
	v_add_u32_e32 v6, 1, v3
	v_cmp_ge_u32_e32 vcc, v5, v4
	s_nop 1
	v_cndmask_b32_e32 v3, v3, v6, vcc
	v_sub_u32_e32 v6, v5, v4
	v_cndmask_b32_e32 v5, v5, v6, vcc
	v_add_u32_e32 v6, 1, v3
	v_cmp_ge_u32_e32 vcc, v5, v4
	v_add_u32_e32 v5, 1, v7
	s_nop 0
	v_cndmask_b32_e32 v3, v3, v6, vcc
	v_mul_lo_u32 v6, v4, v3
	v_add_u32_e32 v4, v6, v4
	v_cmp_ne_u32_e32 vcc, v5, v4
	s_and_saveexec_b64 s[4:5], vcc
	s_xor_b64 s[4:5], exec, s[4:5]
	s_cbranch_execz .LBB0_603
	v_readlane_b32 s6, v251, 34
	v_readlane_b32 s7, v251, 35
	s_waitcnt lgkmcnt(0)
	s_nop 3
	global_load_dword v2, v99, s[6:7] sc1
	s_waitcnt vmcnt(0)
	v_cmp_eq_u32_e32 vcc, v2, v3
	s_and_saveexec_b64 s[6:7], vcc
	s_cbranch_execz .LBB0_602
	s_mov_b32 s20, 1
	s_mov_b64 s[8:9], 0
	s_branch .LBB0_593

; __device__ __forceinline__ unsigned xb_ld(unsigned* p)              { return __hip_atomic_load(p, __ATOMIC_RELAXED, __HIP_MEMORY_SCOPE_AGENT); }
; #define XB_SPIN(cond, bar) do { unsigned _sp = 0; while (cond) { __builtin_amdgcn_s_sleep(1); \
;     if ((++_sp & 255u) == 0u) { if (xb_ld(&(bar)[XB_TMO])) break; if (_sp > XB_SPIN_CAP) { atomicAdd(&(bar)[XB_TMO], 1u); break; } } } } while (0)
; __device__ __forceinline__ void xcd_barrier(const XcdBarrier& b) {
;     ...
;             XB_SPIN(xb_ld(&bar[XB_XGEN(b.x)]) == gen, bar);
.LBB0_595:
	v_readlane_b32 s14, v251, 34
	v_readlane_b32 s15, v251, 35
	s_add_i32 s20, s20, 1
	s_mov_b64 s[16:17], -1
	s_nop 2
	global_load_dword v2, v99, s[14:15] sc1
	s_waitcnt vmcnt(0)
	v_cmp_ne_u32_e32 vcc, v2, v3
	s_orn2_b64 s[14:15], vcc, exec
	s_branch .LBB0_592

; __device__ __forceinline__ unsigned xb_ld(unsigned* p)              { return __hip_atomic_load(p, __ATOMIC_RELAXED, __HIP_MEMORY_SCOPE_AGENT); }
; #define XB_SPIN(cond, bar) do { unsigned _sp = 0; while (cond) { __builtin_amdgcn_s_sleep(1); \
;     if ((++_sp & 255u) == 0u) { if (xb_ld(&(bar)[XB_TMO])) break; if (_sp > XB_SPIN_CAP) { atomicAdd(&(bar)[XB_TMO], 1u); break; } } } } while (0)
; __device__ __forceinline__ void xcd_barrier(const XcdBarrier& b) {
;     ...
;         } else {
;             XB_SPIN(xb_ld(&bar[XB_XGEN(b.x)]) == gen, bar);
;             __builtin_amdgcn_fence(__ATOMIC_ACQUIRE, "agent");
.LBB0_931:
	s_or_b64 exec, exec, s[2:3]
	v_cvt_f32_u32_e32 v6, v4
	s_waitcnt vmcnt(1)
	v_readfirstlane_b32 s2, v5
	v_sub_u32_e32 v5, 0, v4
	v_rcp_iflag_f32_e32 v6, v6
	v_add_u32_e32 v7, s2, v3
	v_mul_f32_e32 v6, 0x4f7ffffe, v6
	v_cvt_u32_f32_e32 v6, v6
	v_mul_lo_u32 v3, v5, v6
	v_mul_hi_u32 v3, v6, v3
	v_add_u32_e32 v3, v6, v3
	v_mul_hi_u32 v3, v7, v3
	v_mul_lo_u32 v5, v3, v4
	v_sub_u32_e32 v5, v7, v5
	v_add_u32_e32 v6, 1, v3
	v_cmp_ge_u32_e32 vcc, v5, v4
	s_nop 1
	v_cndmask_b32_e32 v3, v3, v6, vcc
	v_sub_u32_e32 v6, v5, v4
	v_cndmask_b32_e32 v5, v5, v6, vcc
	v_add_u32_e32 v6, 1, v3
	v_cmp_ge_u32_e32 vcc, v5, v4
	v_add_u32_e32 v5, 1, v7
	s_nop 0
	v_cndmask_b32_e32 v3, v3, v6, vcc
	v_mul_lo_u32 v6, v4, v3
	v_add_u32_e32 v4, v6, v4
	v_cmp_ne_u32_e32 vcc, v5, v4
	s_and_saveexec_b64 s[2:3], vcc
	s_xor_b64 s[2:3], exec, s[2:3]
	s_cbranch_execz .LBB0_945
	v_readlane_b32 s4, v251, 34
	v_readlane_b32 s5, v251, 35
	s_waitcnt lgkmcnt(0)
	s_nop 3
	global_load_dword v2, v99, s[4:5] sc1
	s_waitcnt vmcnt(0)
	v_cmp_eq_u32_e32 vcc, v2, v3
	s_and_saveexec_b64 s[4:5], vcc
	s_cbranch_execz .LBB0_944
	s_mov_b32 s18, 1
	s_mov_b64 s[6:7], 0
	s_branch .LBB0_935

; __device__ __forceinline__ unsigned xb_ld(unsigned* p)              { return __hip_atomic_load(p, __ATOMIC_RELAXED, __HIP_MEMORY_SCOPE_AGENT); }
; #define XB_SPIN(cond, bar) do { unsigned _sp = 0; while (cond) { __builtin_amdgcn_s_sleep(1); \
;     if ((++_sp & 255u) == 0u) { if (xb_ld(&(bar)[XB_TMO])) break; if (_sp > XB_SPIN_CAP) { atomicAdd(&(bar)[XB_TMO], 1u); break; } } } } while (0)
; __device__ __forceinline__ void xcd_barrier(const XcdBarrier& b) {
;     ...
;             XB_SPIN(xb_ld(&bar[XB_XGEN(b.x)]) == gen, bar);
.LBB0_937:
	v_readlane_b32 s12, v251, 34
	v_readlane_b32 s13, v251, 35
	s_add_i32 s18, s18, 1
	s_mov_b64 s[14:15], -1
	s_nop 2
	global_load_dword v2, v99, s[12:13] sc1
	s_waitcnt vmcnt(0)
	v_cmp_ne_u32_e32 vcc, v2, v3
	s_orn2_b64 s[12:13], vcc, exec
	s_branch .LBB0_934
